# rg_b: second unit of each workgroup remapped (n -> 63-n) so every workgroup carries the same total number of chunk steps
# baseline (speedup 1.0000x reference)
; __device__ __forceinline__ float bf2f(unsigned h) { return __uint_as_float(h << 16); }
; __device__ __forceinline__ unsigned pk2(float lo, float hi) { return f2bf(lo) | (f2bf(hi) << 16); }
; __device__ __forceinline__ float sigmf(float x) { return __builtin_amdgcn_rcpf(1.0f + __expf(-x)); }
; __device__ __forceinline__ void rg_b_unit(const Params& p, int unit) {
;     ...
;     for (int tq = 0; tq < 8; ++tq) { const int t = 8 * tq + r8; const size_t o = (size_t)(n * 64 + t) * D;
;         const u32x4 hv = __builtin_nontemporal_load((const u32x4*)(HL + o)), pv = __builtin_nontemporal_load((const u32x4*)(PC + o)), gv = __builtin_nontemporal_load((const u32x4*)(Z + (size_t)t * ZW + 1024)); u32x4 ov;
; #pragma unroll
;         for (int c = 0; c < 4; ++c) { const float h0 = bf2f(hv[c] & 0xffffu) + bf2f(pv[c] & 0xffffu) * carry[2 * c], h1 = bf2f(hv[c] >> 16) + bf2f(pv[c] >> 16) * carry[2 * c + 1];
;             const float g0 = bf2f(gv[c] & 0xffffu), g1 = bf2f(gv[c] >> 16); ov[c] = pk2(h0 * g0 * sigmf(g0), h1 * g1 * sigmf(g1)); }
;         *(u32x4*)(Z + (size_t)t * ZW) = ov; }
.LBB0_218:
	v_lshl_add_u64 v[24:25], v[22:23], 0, v[4:5]
	v_add_co_u32_e64 v66, s[4:5], s31, v24
	v_lshl_add_u64 v[28:29], v[14:15], 0, v[4:5]
	s_nop 0
	v_addc_co_u32_e64 v67, s[4:5], 0, v25, s[4:5]
	v_add_co_u32_e64 v42, s[4:5], s34, v28
	v_lshl_add_u64 v[30:31], v[20:21], 0, v[4:5]
	s_nop 0
	v_addc_co_u32_e64 v43, s[4:5], 0, v29, s[4:5]
	v_add_co_u32_e64 v40, s[4:5], s31, v30
	v_lshl_add_u64 v[32:33], v[16:17], 0, v[4:5]
	s_nop 0
	v_addc_co_u32_e64 v41, s[4:5], 0, v31, s[4:5]
	v_add_co_u32_e64 v38, s[4:5], s35, v28
	v_lshl_add_u64 v[26:27], v[18:19], 0, v[4:5]
	s_nop 0
	v_addc_co_u32_e64 v39, s[4:5], 0, v29, s[4:5]
	v_add_co_u32_e64 v36, s[4:5], s31, v32
	global_load_dwordx4 v[46:49], v[26:27], off nt
	v_add_co_u32_e32 v26, vcc, 0x2000000, v26
	v_addc_co_u32_e64 v37, s[4:5], 0, v33, s[4:5]
	v_add_co_u32_e64 v34, s[4:5], s36, v28
	v_addc_co_u32_e32 v27, vcc, 0, v27, vcc
	s_nop 0
	v_addc_co_u32_e64 v35, s[4:5], 0, v29, s[4:5]
	global_load_dwordx4 v[50:53], v[38:39], off offset:2048 nt
	global_load_dwordx4 v[0:3], v[34:35], off offset:2048 nt
	v_add_co_u32_e32 v68, vcc, 0x400000, v28
	global_load_dwordx4 v[54:57], v[26:27], off nt
	s_nop 0
	v_addc_co_u32_e32 v69, vcc, 0, v29, vcc
	global_load_dwordx4 v[58:61], v[68:69], off offset:2048 nt
	global_load_dwordx4 v[62:65], v[42:43], off offset:2048 nt
	s_add_i32 s10, s10, -4
	v_lshl_add_u64 v[14:15], v[14:15], 0, s[14:15]
	v_lshl_add_u64 v[16:17], v[16:17], 0, s[18:19]
	v_lshl_add_u64 v[18:19], v[18:19], 0, s[18:19]
	v_lshl_add_u64 v[20:21], v[20:21], 0, s[18:19]
	v_lshl_add_u64 v[22:23], v[22:23], 0, s[18:19]
	s_cmp_lg_u32 s10, 0
	s_waitcnt vmcnt(5)
	v_lshlrev_b32_e32 v71, 16, v47
	v_lshlrev_b32_e32 v70, 16, v46
	v_and_b32_e32 v47, 0xffff0000, v47
	v_and_b32_e32 v46, 0xffff0000, v46
	v_lshlrev_b32_e32 v73, 16, v49
	v_lshlrev_b32_e32 v72, 16, v48
	v_and_b32_e32 v49, 0xffff0000, v49
	v_and_b32_e32 v48, 0xffff0000, v48
	s_waitcnt vmcnt(4)
	v_lshlrev_b32_e32 v75, 16, v51
	v_lshlrev_b32_e32 v74, 16, v50
	v_and_b32_e32 v77, 0xffff0000, v51
	v_and_b32_e32 v76, 0xffff0000, v50
	v_lshlrev_b32_e32 v79, 16, v53
	v_lshlrev_b32_e32 v78, 16, v52
	v_and_b32_e32 v81, 0xffff0000, v53
	v_and_b32_e32 v80, 0xffff0000, v52
	s_waitcnt vmcnt(2)
	v_lshlrev_b32_e32 v51, 16, v55
	v_lshlrev_b32_e32 v50, 16, v54
	v_and_b32_e32 v53, 0xffff0000, v55
	v_and_b32_e32 v52, 0xffff0000, v54
	v_lshlrev_b32_e32 v55, 16, v57
	v_lshlrev_b32_e32 v54, 16, v56
	v_mul_f32_e32 v28, 0xbfb8aa3b, v74
	v_mul_f32_e32 v84, 0xbfb8aa3b, v76
	v_mul_f32_e32 v85, 0xbfb8aa3b, v75
	v_mul_f32_e32 v86, 0xbfb8aa3b, v77
	v_mul_f32_e32 v87, 0xbfb8aa3b, v78
	v_mul_f32_e32 v88, 0xbfb8aa3b, v80
	v_mul_f32_e32 v89, 0xbfb8aa3b, v79
	v_mul_f32_e32 v90, 0xbfb8aa3b, v81
	s_waitcnt vmcnt(1)
	v_lshlrev_b32_e32 v83, 16, v59
	v_lshlrev_b32_e32 v82, 16, v58
	v_and_b32_e32 v59, 0xffff0000, v59
	v_and_b32_e32 v58, 0xffff0000, v58
	v_pk_fma_f32 v[50:51], v[8:9], v[50:51], v[70:71]
	v_pk_fma_f32 v[46:47], v[10:11], v[52:53], v[46:47]
	v_lshlrev_b32_e32 v53, 16, v61
	v_lshlrev_b32_e32 v52, 16, v60
	v_and_b32_e32 v61, 0xffff0000, v61
	v_and_b32_e32 v60, 0xffff0000, v60
	v_pk_fma_f32 v[54:55], v[6:7], v[54:55], v[72:73]
	v_exp_f32_e32 v28, v28
	v_exp_f32_e32 v72, v84
	v_exp_f32_e32 v73, v85
	v_exp_f32_e32 v84, v86
	v_exp_f32_e32 v85, v87
	v_exp_f32_e32 v86, v88
	v_exp_f32_e32 v87, v89
	v_exp_f32_e32 v88, v90
	v_mul_f32_e32 v89, 0xbfb8aa3b, v82
	v_mul_f32_e32 v90, 0xbfb8aa3b, v58
	v_pk_mul_f32 v[50:51], v[50:51], v[82:83]
	v_mul_f32_e32 v82, 0xbfb8aa3b, v83
	v_pk_mul_f32 v[46:47], v[46:47], v[58:59]
	v_mul_f32_e32 v58, 0xbfb8aa3b, v59
	v_mul_f32_e32 v59, 0xbfb8aa3b, v52
	v_mul_f32_e32 v83, 0xbfb8aa3b, v60
	v_pk_mul_f32 v[54:55], v[54:55], v[52:53]
	v_mul_f32_e32 v52, 0xbfb8aa3b, v53
	v_mul_f32_e32 v53, 0xbfb8aa3b, v61
	v_and_b32_e32 v57, 0xffff0000, v57
	v_and_b32_e32 v56, 0xffff0000, v56
	v_exp_f32_e32 v89, v89
	v_exp_f32_e32 v90, v90
	v_exp_f32_e32 v97, v82
	v_exp_f32_e32 v98, v58
	v_exp_f32_e32 v99, v59
	v_exp_f32_e32 v100, v83
	v_exp_f32_e32 v52, v52
	v_exp_f32_e32 v53, v53
	v_pk_fma_f32 v[48:49], v[12:13], v[56:57], v[48:49]
	s_waitcnt vmcnt(0)
	v_lshlrev_b32_e32 v56, 16, v62
	v_and_b32_e32 v62, 0xffff0000, v62
	v_pk_mul_f32 v[48:49], v[48:49], v[60:61]
	v_mul_f32_e32 v61, 0xbfb8aa3b, v62
	v_mul_f32_e32 v60, 0xbfb8aa3b, v56
	v_exp_f32_e32 v102, v61
	v_add_f32_e32 v28, 1.0, v28
	v_add_f32_e32 v59, 1.0, v72
	v_add_f32_e32 v61, 1.0, v73
	v_add_f32_e32 v72, 1.0, v84
	v_add_f32_e32 v73, 1.0, v85
	v_add_f32_e32 v83, 1.0, v87
	v_add_f32_e32 v84, 1.0, v88
	v_exp_f32_e32 v101, v60
	v_add_f32_e32 v82, 1.0, v86
	v_rcp_f32_e32 v58, v28
	v_rcp_f32_e32 v60, v59
	v_rcp_f32_e32 v59, v61
	v_rcp_f32_e32 v61, v72
	v_rcp_f32_e32 v72, v73
	v_rcp_f32_e32 v73, v83
	v_rcp_f32_e32 v83, v84
	v_add_f32_e32 v28, 1.0, v89
	v_add_f32_e32 v84, 1.0, v90
	v_add_f32_e32 v85, 1.0, v97
	v_add_f32_e32 v86, 1.0, v98
	v_add_f32_e32 v87, 1.0, v99
	v_add_f32_e32 v88, 1.0, v100
	v_add_f32_e32 v89, 1.0, v52
	v_add_f32_e32 v90, 1.0, v53
	v_rcp_f32_e32 v52, v28
	v_rcp_f32_e32 v53, v85
	v_rcp_f32_e32 v85, v86
	v_rcp_f32_e32 v86, v87
	v_rcp_f32_e32 v88, v88
	v_rcp_f32_e32 v87, v89
	v_rcp_f32_e32 v89, v90
	v_rcp_f32_e32 v84, v84
	v_pk_mul_f32 v[50:51], v[50:51], v[52:53]
	v_pk_mul_f32 v[52:53], v[54:55], v[86:87]
	v_pk_mul_f32 v[48:49], v[48:49], v[88:89]
	v_pk_mul_f32 v[46:47], v[46:47], v[84:85]
	v_bfe_u32 v28, v49, 16, 1
	v_bfe_u32 v85, v50, 16, 1
	v_bfe_u32 v86, v51, 16, 1
	v_bfe_u32 v87, v52, 16, 1
	v_bfe_u32 v88, v53, 16, 1
	v_bfe_u32 v54, v48, 16, 1
	v_bfe_u32 v55, v47, 16, 1
	v_bfe_u32 v84, v46, 16, 1
	v_add3_u32 v28, v49, v28, s33
	v_add3_u32 v49, v53, v88, s33
	v_add3_u32 v52, v52, v87, s33
; __device__ __forceinline__ float bf2f(unsigned h) { return __uint_as_float(h << 16); }
; __device__ __forceinline__ unsigned pk2(float lo, float hi) { return f2bf(lo) | (f2bf(hi) << 16); }
; __device__ __forceinline__ float sigmf(float x) { return __builtin_amdgcn_rcpf(1.0f + __expf(-x)); }
; __device__ __forceinline__ void rg_b_unit(const Params& p, int unit) {
;     ...
;     for (int tq = 0; tq < 8; ++tq) { const int t = 8 * tq + r8; const size_t o = (size_t)(n * 64 + t) * D;
;         const u32x4 hv = __builtin_nontemporal_load((const u32x4*)(HL + o)), pv = __builtin_nontemporal_load((const u32x4*)(PC + o)), gv = __builtin_nontemporal_load((const u32x4*)(Z + (size_t)t * ZW + 1024)); u32x4 ov;
; #pragma unroll
;         for (int c = 0; c < 4; ++c) { const float h0 = bf2f(hv[c] & 0xffffu) + bf2f(pv[c] & 0xffffu) * carry[2 * c], h1 = bf2f(hv[c] >> 16) + bf2f(pv[c] >> 16) * carry[2 * c + 1];
;             const float g0 = bf2f(gv[c] & 0xffffu), g1 = bf2f(gv[c] >> 16); ov[c] = pk2(h0 * g0 * sigmf(g0), h1 * g1 * sigmf(g1)); }
;         *(u32x4*)(Z + (size_t)t * ZW) = ov; }
	v_add3_u32 v51, v51, v86, s33
	v_add3_u32 v50, v50, v85, s33
	v_add3_u32 v46, v46, v84, s33
	v_add3_u32 v47, v47, v55, s33
	v_add3_u32 v48, v48, v54, s33
	v_lshrrev_b32_e32 v50, 16, v50
	v_lshrrev_b32_e32 v51, 16, v51
	v_lshrrev_b32_e32 v52, 16, v52
	v_lshrrev_b32_e32 v49, 16, v49
	v_and_or_b32 v49, v28, s29, v49
	v_and_or_b32 v48, v48, s29, v52
	v_and_or_b32 v47, v47, s29, v51
	v_and_or_b32 v46, v46, s29, v50
	global_store_dwordx4 v[68:69], v[46:49], off
	global_load_dwordx4 v[46:49], v[24:25], off nt
	s_nop 0
	global_load_dwordx4 v[50:53], v[66:67], off nt
	v_lshlrev_b32_e32 v57, 16, v63
	v_lshlrev_b32_e32 v71, 16, v65
	v_lshlrev_b32_e32 v70, 16, v64
	v_and_b32_e32 v65, 0xffff0000, v65
	v_and_b32_e32 v64, 0xffff0000, v64
	v_and_b32_e32 v63, 0xffff0000, v63
	v_mul_f32_e32 v91, 0xbfb8aa3b, v57
	v_mul_f32_e32 v93, 0xbfb8aa3b, v70
	v_mul_f32_e32 v94, 0xbfb8aa3b, v64
	v_mul_f32_e32 v95, 0xbfb8aa3b, v71
	v_mul_f32_e32 v96, 0xbfb8aa3b, v65
	v_mul_f32_e32 v92, 0xbfb8aa3b, v63
	v_exp_f32_e32 v91, v91
	v_exp_f32_e32 v93, v93
	v_exp_f32_e32 v94, v94
	v_exp_f32_e32 v95, v95
	v_exp_f32_e32 v96, v96
	v_exp_f32_e32 v92, v92
	v_add_f32_e32 v97, 1.0, v101
	v_add_f32_e32 v98, 1.0, v102
	v_add_f32_e32 v91, 1.0, v91
	v_add_f32_e32 v100, 1.0, v93
	v_add_f32_e32 v101, 1.0, v94
	v_add_f32_e32 v95, 1.0, v95
	v_add_f32_e32 v102, 1.0, v96
	v_add_f32_e32 v99, 1.0, v92
	v_rcp_f32_e32 v90, v97
	v_rcp_f32_e32 v91, v91
	v_rcp_f32_e32 v94, v100
	v_rcp_f32_e32 v96, v101
	v_rcp_f32_e32 v95, v95
	v_rcp_f32_e32 v97, v102
	v_rcp_f32_e32 v92, v98
	v_rcp_f32_e32 v93, v99
	v_rcp_f32_e32 v82, v82
	v_lshlrev_b32_e32 v27, 16, v1
	v_lshlrev_b32_e32 v26, 16, v0
	v_and_b32_e32 v0, 0xffff0000, v0
	v_lshlrev_b32_e32 v29, 16, v3
	v_and_b32_e32 v1, 0xffff0000, v1
	v_and_b32_e32 v3, 0xffff0000, v3
	s_waitcnt vmcnt(1)
	v_lshlrev_b32_e32 v25, 16, v47
	v_lshlrev_b32_e32 v24, 16, v46
	s_waitcnt vmcnt(0)
	v_lshlrev_b32_e32 v55, 16, v51
	v_lshlrev_b32_e32 v54, 16, v50
	v_and_b32_e32 v47, 0xffff0000, v47
	v_and_b32_e32 v46, 0xffff0000, v46
	v_and_b32_e32 v51, 0xffff0000, v51
	v_and_b32_e32 v50, 0xffff0000, v50
	v_lshlrev_b32_e32 v67, 16, v49
	v_lshlrev_b32_e32 v66, 16, v48
	v_lshlrev_b32_e32 v69, 16, v53
	v_lshlrev_b32_e32 v68, 16, v52
	v_and_b32_e32 v49, 0xffff0000, v49
	v_and_b32_e32 v48, 0xffff0000, v48
	v_and_b32_e32 v53, 0xffff0000, v53
	v_and_b32_e32 v52, 0xffff0000, v52
	v_pk_fma_f32 v[24:25], v[8:9], v[54:55], v[24:25]
	v_pk_fma_f32 v[46:47], v[10:11], v[50:51], v[46:47]
	v_pk_fma_f32 v[50:51], v[6:7], v[68:69], v[66:67]
	v_pk_fma_f32 v[48:49], v[12:13], v[52:53], v[48:49]
	v_pk_mul_f32 v[24:25], v[24:25], v[56:57]
	v_pk_mul_f32 v[50:51], v[50:51], v[70:71]
	v_pk_mul_f32 v[48:49], v[48:49], v[64:65]
	v_pk_mul_f32 v[46:47], v[46:47], v[62:63]
	v_pk_mul_f32 v[24:25], v[24:25], v[90:91]
	v_pk_mul_f32 v[50:51], v[50:51], v[94:95]
	v_pk_mul_f32 v[48:49], v[48:49], v[96:97]
	v_pk_mul_f32 v[46:47], v[46:47], v[92:93]
	v_bfe_u32 v28, v49, 16, 1
	v_bfe_u32 v55, v24, 16, 1
	v_bfe_u32 v56, v25, 16, 1
	v_bfe_u32 v57, v50, 16, 1
	v_bfe_u32 v62, v51, 16, 1
	v_bfe_u32 v52, v48, 16, 1
	v_bfe_u32 v53, v47, 16, 1
	v_bfe_u32 v54, v46, 16, 1
	v_add3_u32 v28, v49, v28, s33
	v_add3_u32 v49, v51, v62, s33
	v_add3_u32 v50, v50, v57, s33
	v_add3_u32 v25, v25, v56, s33
	v_add3_u32 v24, v24, v55, s33
	v_add3_u32 v46, v46, v54, s33
	v_add3_u32 v47, v47, v53, s33
	v_add3_u32 v48, v48, v52, s33
	v_lshrrev_b32_e32 v24, 16, v24
	v_lshrrev_b32_e32 v25, 16, v25
	v_lshrrev_b32_e32 v50, 16, v50
	v_lshrrev_b32_e32 v49, 16, v49
	v_and_or_b32 v49, v28, s29, v49
	v_and_or_b32 v48, v48, s29, v50
	v_and_or_b32 v47, v47, s29, v25
	v_and_or_b32 v46, v46, s29, v24
	global_store_dwordx4 v[42:43], v[46:49], off
	global_load_dwordx4 v[46:49], v[30:31], off nt
	s_nop 0
	global_load_dwordx4 v[50:53], v[40:41], off nt
	s_waitcnt vmcnt(1)
	v_lshlrev_b32_e32 v25, 16, v47
	v_lshlrev_b32_e32 v24, 16, v46
	s_waitcnt vmcnt(0)
; __device__ __forceinline__ float bf2f(unsigned h) { return __uint_as_float(h << 16); }
; __device__ __forceinline__ unsigned pk2(float lo, float hi) { return f2bf(lo) | (f2bf(hi) << 16); }
; __device__ __forceinline__ float sigmf(float x) { return __builtin_amdgcn_rcpf(1.0f + __expf(-x)); }
; __device__ __forceinline__ void rg_b_unit(const Params& p, int unit) {
;     ...
;     for (int tq = 0; tq < 8; ++tq) { const int t = 8 * tq + r8; const size_t o = (size_t)(n * 64 + t) * D;
;         const u32x4 hv = __builtin_nontemporal_load((const u32x4*)(HL + o)), pv = __builtin_nontemporal_load((const u32x4*)(PC + o)), gv = __builtin_nontemporal_load((const u32x4*)(Z + (size_t)t * ZW + 1024)); u32x4 ov;
; #pragma unroll
;         for (int c = 0; c < 4; ++c) { const float h0 = bf2f(hv[c] & 0xffffu) + bf2f(pv[c] & 0xffffu) * carry[2 * c], h1 = bf2f(hv[c] >> 16) + bf2f(pv[c] >> 16) * carry[2 * c + 1];
;             const float g0 = bf2f(gv[c] & 0xffffu), g1 = bf2f(gv[c] >> 16); ov[c] = pk2(h0 * g0 * sigmf(g0), h1 * g1 * sigmf(g1)); }
;         *(u32x4*)(Z + (size_t)t * ZW) = ov; }
; __global__ void __launch_bounds__(NT, 2) mk_fwd(Params p) {
;     ...
;     for (int u = bid; u < 512; u += G) rg_b_unit(p, u);
	v_lshlrev_b32_e32 v31, 16, v51
	v_lshlrev_b32_e32 v30, 16, v50
	v_and_b32_e32 v41, 0xffff0000, v47
	v_and_b32_e32 v40, 0xffff0000, v46
	v_and_b32_e32 v43, 0xffff0000, v51
	v_and_b32_e32 v42, 0xffff0000, v50
	v_lshlrev_b32_e32 v47, 16, v49
	v_lshlrev_b32_e32 v46, 16, v48
	v_lshlrev_b32_e32 v51, 16, v53
	v_lshlrev_b32_e32 v50, 16, v52
	v_and_b32_e32 v49, 0xffff0000, v49
	v_and_b32_e32 v48, 0xffff0000, v48
	v_and_b32_e32 v53, 0xffff0000, v53
	v_and_b32_e32 v52, 0xffff0000, v52
	v_pk_fma_f32 v[24:25], v[8:9], v[30:31], v[24:25]
	v_pk_fma_f32 v[30:31], v[10:11], v[42:43], v[40:41]
	v_pk_fma_f32 v[40:41], v[6:7], v[50:51], v[46:47]
	v_pk_fma_f32 v[42:43], v[12:13], v[52:53], v[48:49]
	v_pk_mul_f32 v[24:25], v[24:25], v[74:75]
	v_pk_mul_f32 v[40:41], v[40:41], v[78:79]
	v_pk_mul_f32 v[30:31], v[30:31], v[76:77]
	v_pk_mul_f32 v[42:43], v[42:43], v[80:81]
	v_pk_mul_f32 v[24:25], v[24:25], v[58:59]
	v_pk_mul_f32 v[40:41], v[40:41], v[72:73]
	v_pk_mul_f32 v[30:31], v[30:31], v[60:61]
	v_pk_mul_f32 v[42:43], v[42:43], v[82:83]
	v_bfe_u32 v49, v24, 16, 1
	v_bfe_u32 v50, v25, 16, 1
	v_bfe_u32 v51, v40, 16, 1
	v_bfe_u32 v52, v41, 16, 1
	v_bfe_u32 v28, v43, 16, 1
	v_bfe_u32 v46, v42, 16, 1
	v_bfe_u32 v47, v31, 16, 1
	v_bfe_u32 v48, v30, 16, 1
	v_add3_u32 v41, v41, v52, s33
	v_add3_u32 v40, v40, v51, s33
	v_add3_u32 v25, v25, v50, s33
	v_add3_u32 v24, v24, v49, s33
	v_add3_u32 v30, v30, v48, s33
	v_add3_u32 v31, v31, v47, s33
	v_add3_u32 v42, v42, v46, s33
	v_add3_u32 v28, v43, v28, s33
	v_lshrrev_b32_e32 v24, 16, v24
	v_lshrrev_b32_e32 v25, 16, v25
	v_lshrrev_b32_e32 v40, 16, v40
	v_lshrrev_b32_e32 v41, 16, v41
	v_and_or_b32 v43, v28, s29, v41
	v_and_or_b32 v42, v42, s29, v40
	v_and_or_b32 v41, v31, s29, v25
	v_and_or_b32 v40, v30, s29, v24
	global_store_dwordx4 v[38:39], v[40:43], off
	global_load_dwordx4 v[38:41], v[32:33], off nt
	s_nop 0
	global_load_dwordx4 v[46:49], v[36:37], off nt
	v_lshlrev_b32_e32 v28, 16, v2
	v_and_b32_e32 v2, 0xffff0000, v2
	v_mul_f32_e32 v24, 0xbfb8aa3b, v26
	v_mul_f32_e32 v25, 0xbfb8aa3b, v0
	v_mul_f32_e32 v30, 0xbfb8aa3b, v27
	v_mul_f32_e32 v32, 0xbfb8aa3b, v28
	v_mul_f32_e32 v33, 0xbfb8aa3b, v2
	v_mul_f32_e32 v36, 0xbfb8aa3b, v29
	v_mul_f32_e32 v31, 0xbfb8aa3b, v1
	v_mul_f32_e32 v37, 0xbfb8aa3b, v3
	v_exp_f32_e32 v24, v24
	v_exp_f32_e32 v25, v25
	v_exp_f32_e32 v30, v30
	v_exp_f32_e32 v32, v32
	v_exp_f32_e32 v33, v33
	v_exp_f32_e32 v36, v36
	v_exp_f32_e32 v31, v31
	v_exp_f32_e32 v37, v37
	v_add_f32_e32 v24, 1.0, v24
	v_add_f32_e32 v25, 1.0, v25
	v_add_f32_e32 v42, 1.0, v30
	v_add_f32_e32 v32, 1.0, v32
	v_add_f32_e32 v33, 1.0, v33
	v_add_f32_e32 v43, 1.0, v36
	v_add_f32_e32 v31, 1.0, v31
	v_add_f32_e32 v37, 1.0, v37
	v_rcp_f32_e32 v24, v24
	v_rcp_f32_e32 v30, v25
	v_rcp_f32_e32 v25, v42
	v_rcp_f32_e32 v32, v32
	v_rcp_f32_e32 v36, v33
	v_rcp_f32_e32 v33, v43
	v_rcp_f32_e32 v31, v31
	v_rcp_f32_e32 v37, v37
	s_waitcnt vmcnt(1)
	v_lshlrev_b32_e32 v43, 16, v39
	v_lshlrev_b32_e32 v42, 16, v38
	s_waitcnt vmcnt(0)
	v_lshlrev_b32_e32 v51, 16, v47
	v_lshlrev_b32_e32 v50, 16, v46
	v_and_b32_e32 v39, 0xffff0000, v39
	v_and_b32_e32 v38, 0xffff0000, v38
	v_and_b32_e32 v47, 0xffff0000, v47
	v_and_b32_e32 v46, 0xffff0000, v46
	v_lshlrev_b32_e32 v53, 16, v41
	v_lshlrev_b32_e32 v52, 16, v40
	v_lshlrev_b32_e32 v55, 16, v49
	v_lshlrev_b32_e32 v54, 16, v48
	v_and_b32_e32 v41, 0xffff0000, v41
	v_and_b32_e32 v40, 0xffff0000, v40
	v_and_b32_e32 v49, 0xffff0000, v49
	v_and_b32_e32 v48, 0xffff0000, v48
	v_pk_fma_f32 v[42:43], v[8:9], v[50:51], v[42:43]
	v_pk_fma_f32 v[38:39], v[10:11], v[46:47], v[38:39]
	v_pk_fma_f32 v[46:47], v[6:7], v[54:55], v[52:53]
	v_pk_fma_f32 v[40:41], v[12:13], v[48:49], v[40:41]
	v_pk_mul_f32 v[26:27], v[42:43], v[26:27]
	v_pk_mul_f32 v[28:29], v[46:47], v[28:29]
	v_pk_mul_f32 v[0:1], v[38:39], v[0:1]
	v_pk_mul_f32 v[2:3], v[40:41], v[2:3]
	v_pk_mul_f32 v[24:25], v[26:27], v[24:25]
	v_pk_mul_f32 v[26:27], v[28:29], v[32:33]
	v_pk_mul_f32 v[0:1], v[0:1], v[30:31]
	v_pk_mul_f32 v[2:3], v[2:3], v[36:37]
	v_bfe_u32 v32, v24, 16, 1
	v_bfe_u32 v33, v25, 16, 1
	v_bfe_u32 v36, v26, 16, 1
	v_bfe_u32 v37, v27, 16, 1
	v_bfe_u32 v28, v3, 16, 1
	v_bfe_u32 v29, v2, 16, 1
	v_bfe_u32 v30, v1, 16, 1
	v_bfe_u32 v31, v0, 16, 1
	v_add3_u32 v27, v27, v37, s33
	v_add3_u32 v26, v26, v36, s33
	v_add3_u32 v25, v25, v33, s33
	v_add3_u32 v24, v24, v32, s33
	v_add3_u32 v0, v0, v31, s33
	v_add3_u32 v1, v1, v30, s33
	v_add3_u32 v2, v2, v29, s33
	v_add3_u32 v3, v3, v28, s33
	v_lshrrev_b32_e32 v24, 16, v24
	v_lshrrev_b32_e32 v25, 16, v25
	v_lshrrev_b32_e32 v26, 16, v26
	v_lshrrev_b32_e32 v27, 16, v27
	v_and_or_b32 v3, v3, s29, v27
	v_and_or_b32 v2, v2, s29, v26
	v_and_or_b32 v1, v1, s29, v25
	v_and_or_b32 v0, v0, s29, v24
	global_store_dwordx4 v[34:35], v[0:3], off
	s_cbranch_scc1 .LBB0_218
	s_add_i32 s37, s37, s52
	s_xor_b32 s37, s37, 0x7e
	s_add_i32 s25, s25, s26
	s_cmpk_gt_i32 s37, 0x1ff
	s_cbranch_scc0 .LBB0_209
